# v68 + attention ALiBi/mask: out-of-range deltas pre-set to +inf so the per-unit mask selects and their 100 spilled-SGPR reloads go; first-block key tiles invalidated by a wave-uniform branch
# speedup vs baseline: 1.0463x; 1.0104x over previous
; #define LAS __attribute__((address_space(3)))
; __device__ __forceinline__ void attn_phase(const Params& p, LAS unsigned char* lds, int tid, int G, int bid) {
;     ...
;         const int tstart = w & ~1;
;         f32x4 s[10];
; #pragma unroll
;         for (int tt = 0; tt < 10; ++tt) { const LAS unsigned char* kp = lds + (16 * (tstart + tt) + fr) * KS_PITCH + quad * 8;
;             const long k0 = *(const LAS long*)kp, k1 = *(const LAS long*)(kp + 32);
;             f32x4 a = {0.f, 0.f, 0.f, 0.f};
;             a = __builtin_amdgcn_mfma_f32_16x16x32_fp8_fp8(k0, q0, a, 0, 0, 0);
;             s[tt] = __builtin_amdgcn_mfma_f32_16x16x32_fp8_fp8(k1, q1, a, 0, 0, 0) * C2; }
;         const float sl2 = __builtin_amdgcn_exp2f(-8.0f * (float)(head + 1) / 12.0f) * (float)d * LOG2E;
;         float mx = -INFINITY;
; #pragma unroll
;         for (int tt = 0; tt < 10; ++tt)
; #pragma unroll
;             for (int j = 0; j < 4; ++j) { const int kj = 16 * (tstart + tt) + 4 * quad + j, delta = qi + 128 - kj;
;                 const bool valid = (delta >= 0) && (delta <= 128) && (nb > 0 || kj >= 128);
;                 const float v = valid ? s[tt][j] - sl2 * (float)delta : -INFINITY; s[tt][j] = v; mx = fmaxf(mx, v); }
.LBB0_269:
	s_or_b64 exec, exec, s[4:5]
	s_ashr_i32 s4, s10, 6
	s_lshl_b32 s5, s4, 4
	v_and_b32_e32 v41, 15, v144
	s_add_i32 s6, s5, s8
	v_add_u32_e32 v20, s6, v41
	v_ashrrev_i32_e32 v21, 31, v20
	v_bfe_u32 v22, v144, 4, 2
	v_lshlrev_b64 v[20:21], 6, v[20:21]
	v_lshl_add_u64 v[20:21], s[0:1], 0, v[20:21]
	v_lshlrev_b32_e32 v90, 3, v22
	v_mov_b32_e32 v91, v8
	v_lshl_add_u64 v[20:21], v[20:21], 0, v[90:91]
	global_load_dwordx2 v[60:61], v[20:21], off offset:32
	global_load_dwordx2 v[62:63], v[20:21], off
	v_lshlrev_b32_e32 v20, 2, v22
	v_mbcnt_lo_u32_b32 v22, -1, 0
	v_mbcnt_hi_u32_b32 v22, -1, v22
	v_and_b32_e32 v27, 64, v22
	s_add_i32 s0, s4, s3
	v_xor_b32_e32 v23, 16, v22
	v_add_u32_e32 v27, 64, v27
	v_writelane_b32 v250, s0, 34
	s_lshl_b32 s0, s4, 9
	v_cmp_lt_i32_e32 vcc, v23, v27
	v_and_b32_e32 v24, 63, v144
	s_and_b32 s0, s0, 0x200
	v_cndmask_b32_e32 v23, v22, v23, vcc
	s_mulk_i32 s4, 0x900
	v_lshl_or_b32 v94, v24, 3, s0
	v_lshlrev_b32_e32 v122, 2, v23
	v_xor_b32_e32 v23, 32, v22
	s_add_i32 s0, s4, 0
	v_cmp_lt_i32_e32 vcc, v23, v27
	s_add_i32 s0, s0, 0x12000
	v_cmp_gt_u32_e64 s[6:7], 16, v24
	v_cndmask_b32_e32 v22, v22, v23, vcc
	v_mov_b32_e32 v23, s0
	s_movk_i32 s0, 0x110
	s_movk_i32 s1, 0x50
	v_bfe_u32 v27, v144, 2, 4
	v_writelane_b32 v250, s6, 35
	v_mul_lo_u32 v35, v86, s0
	v_mul_lo_u32 v36, v88, s0
	s_and_b32 s0, s5, 0xffffffe0
	v_or_b32_e32 v92, s5, v41
	v_lshlrev_b32_e32 v123, 2, v22
	v_mad_u32_u24 v22, v41, s1, v23
	v_or_b32_e32 v124, s5, v27
	v_mad_u32_u24 v23, v27, s1, v23
	v_writelane_b32 v250, s7, 36
	v_or_b32_e32 v27, s0, v41
	s_or_b32 s8, s5, 16
	s_add_i32 s9, s0, 32
	s_add_i32 s10, s0, 48
	s_add_i32 s11, s0, 64
	s_add_i32 s12, s0, 0x50
	s_add_i32 s13, s0, 0x60
	s_add_i32 s7, s0, 0x70
	s_add_i32 s6, s0, 0x80
	s_add_i32 s4, s0, 0x90
	v_add_u32_e32 v42, 0x80, v92
	v_mul_lo_u32 v29, v27, s1
	v_or_b32_e32 v27, s8, v41
	v_or_b32_e32 v28, s9, v41
	v_or_b32_e32 v30, s10, v41
	v_or_b32_e32 v31, s11, v41
	v_or_b32_e32 v32, s12, v41
	v_or_b32_e32 v37, s13, v41
	v_or_b32_e32 v38, s7, v41
	v_or_b32_e32 v39, s6, v41
	v_or_b32_e32 v40, s4, v41
	v_or_b32_e32 v44, s0, v20
	v_mul_lo_u32 v33, v120, s1
	v_mul_lo_u32 v34, v121, s1
	v_mul_lo_u32 v27, v27, s1
	v_mul_lo_u32 v28, v28, s1
	v_mul_lo_u32 v30, v30, s1
	v_mul_lo_u32 v31, v31, s1
	v_mul_lo_u32 v32, v32, s1
	v_mul_lo_u32 v37, v37, s1
	v_mul_lo_u32 v38, v38, s1
	v_mul_lo_u32 v39, v39, s1
	v_mul_lo_u32 v40, v40, s1
	v_sub_u32_e32 v45, v42, v44
	s_movk_i32 s1, 0x81
	v_cmp_gt_u32_e64 s[14:15], s1, v45
	s_movk_i32 s3, 0x7f
	v_cvt_f32_u32_e32 v125, v45
	v_writelane_b32 v250, s14, 37
	v_xad_u32 v45, v44, -1, v42
	s_movk_i32 s5, 0x7e
	v_writelane_b32 v250, s15, 38
	v_cmp_lt_i32_e64 s[14:15], s3, v44
	v_cvt_f32_u32_e32 v126, v45
	v_add_u32_e32 v21, 0, v90
	v_writelane_b32 v250, s14, 39
	v_sub_u32_e32 v43, v21, v20
	v_lshlrev_b32_e32 v24, 2, v94
	v_writelane_b32 v250, s15, 40
	v_cmp_gt_u32_e64 s[14:15], s1, v45
	v_or_b32_e32 v45, 2, v44
	v_sub_u32_e32 v46, v42, v45
	v_writelane_b32 v250, s14, 41
	v_cvt_f32_u32_e32 v127, v46
	v_ashrrev_i32_e32 v93, 31, v92
	v_writelane_b32 v250, s15, 42
	v_cmp_lt_i32_e64 s[14:15], s5, v44
	v_or_b32_e32 v44, 3, v44
	v_add_u32_e32 v26, 0, v84
	v_writelane_b32 v250, s14, 43
	v_add_u32_sdwa v25, v8, v144 dst_sel:DWORD dst_unused:UNUSED_PAD src0_sel:DWORD src1_sel:BYTE_0
	v_mul_u32_u24_e32 v41, 0x110, v41
	v_writelane_b32 v250, s15, 44
	v_cmp_gt_u32_e64 s[14:15], s1, v46
	v_add_u32_e32 v181, v22, v20
	v_add_u32_e32 v166, v26, v34
	v_writelane_b32 v250, s14, 45
	v_add_u32_e32 v167, v25, v35
	v_add_u32_e32 v168, v25, v36
	v_writelane_b32 v250, s15, 46
	v_cmp_lt_i32_e64 s[14:15], s3, v45
	v_sub_u32_e32 v45, v42, v44
	v_cvt_f32_u32_e32 v128, v45
	v_writelane_b32 v250, s14, 47
	v_add_u32_e32 v169, v21, v29
	v_add_u32_e32 v171, v21, v27
	v_writelane_b32 v250, s15, 48
	v_cmp_gt_u32_e64 s[14:15], s1, v45
	v_add_u32_e32 v172, v21, v28
	v_add_u32_e32 v173, v21, v30
	v_writelane_b32 v250, s14, 49
	v_add_u32_e32 v174, v21, v31
	v_add_u32_e32 v175, v21, v32
	v_writelane_b32 v250, s15, 50
	v_cmp_lt_i32_e64 s[14:15], s3, v44
	v_or_b32_e32 v44, s8, v20
	v_sub_u32_e32 v45, v42, v44
	v_writelane_b32 v250, s14, 51
	v_cvt_f32_u32_e32 v129, v45
	v_add_u32_e32 v176, v21, v37
	v_writelane_b32 v250, s15, 52
	v_cmp_gt_u32_e64 s[14:15], s1, v45
	v_xad_u32 v45, v44, -1, v42
	v_cvt_f32_u32_e32 v130, v45
	v_writelane_b32 v250, s14, 53
	v_add_u32_e32 v177, v21, v38
	v_add_u32_e32 v178, v21, v39
	v_writelane_b32 v250, s15, 54
	v_cmp_lt_i32_e64 s[14:15], s3, v44
	v_add_u32_e32 v179, v21, v40
	v_add_u32_e32 v182, v23, v84
	v_writelane_b32 v250, s14, 55
	v_mov_b64_e32 v[38:39], v[10:11]
	v_mov_b64_e32 v[30:31], v[10:11]
	v_writelane_b32 v250, s15, 56
	v_cmp_gt_u32_e64 s[14:15], s1, v45
	v_or_b32_e32 v45, 2, v44
	v_sub_u32_e32 v46, v42, v45
	v_writelane_b32 v250, s14, 57
	v_cvt_f32_u32_e32 v131, v46
	v_mov_b64_e32 v[50:51], v[10:11]
	v_writelane_b32 v250, s15, 58
	v_cmp_lt_i32_e64 s[14:15], s5, v44
	v_or_b32_e32 v44, 3, v44
	v_mov_b64_e32 v[58:59], v[10:11]
	v_writelane_b32 v250, s14, 59
	v_mov_b64_e32 v[54:55], v[10:11]
	v_mov_b32_e32 v95, v8
	v_writelane_b32 v250, s15, 60
	v_cmp_gt_u32_e64 s[14:15], s1, v46
	s_mov_b32 s80, 0x3e38aa3b
	s_mov_b32 s81, 0xc3e00000
	v_writelane_b32 v250, s14, 61
	v_mov_b32_e32 v184, 0xff800000
	v_mov_b32_e32 v185, 0x43e00000
	v_writelane_b32 v250, s15, 62
	v_cmp_lt_i32_e64 s[14:15], s3, v45
	v_sub_u32_e32 v45, v42, v44
	v_cvt_f32_u32_e32 v132, v45
	v_writelane_b32 v250, s14, 63
	v_mov_b64_e32 v[36:37], v[8:9]
	v_mov_b64_e32 v[28:29], v[8:9]
	v_writelane_b32 v249, s15, 0
	v_cmp_gt_u32_e64 s[14:15], s1, v45
	v_mov_b64_e32 v[48:49], v[8:9]
	v_mov_b64_e32 v[56:57], v[8:9]
	v_writelane_b32 v249, s14, 1
	v_mov_b64_e32 v[52:53], v[8:9]
	s_waitcnt vmcnt(0)
; __device__ __forceinline__ void attn_phase(const Params& p, LAS unsigned char* lds, int tid, int G, int bid) {
;     ...
;             for (int j = 0; j < 4; ++j) { const int kj = 16 * (tstart + tt) + 4 * quad + j, delta = qi + 128 - kj;
;                 const bool valid = (delta >= 0) && (delta <= 128) && (nb > 0 || kj >= 128);
;                 const float v = valid ? s[tt][j] - sl2 * (float)delta : -INFINITY; s[tt][j] = v; mx = fmaxf(mx, v); }
	v_mov_b64_e32 v[100:101], v[62:63]
	v_writelane_b32 v249, s15, 2
	v_cmp_lt_i32_e64 s[14:15], s3, v44
	v_or_b32_e32 v44, s9, v20
	v_sub_u32_e32 v45, v42, v44
	v_writelane_b32 v249, s14, 3
	v_cmp_gt_u32_e64 s[8:9], s1, v45
	v_cvt_f32_u32_e32 v133, v45
	v_writelane_b32 v249, s15, 4
	v_writelane_b32 v249, s8, 5
	v_xad_u32 v45, v44, -1, v42
	v_cvt_f32_u32_e32 v134, v45
	v_writelane_b32 v249, s9, 6
	v_cmp_lt_i32_e64 s[8:9], s3, v44
	v_mov_b64_e32 v[102:103], v[60:61]
	s_nop 0
	v_writelane_b32 v249, s8, 7
	s_nop 1
	v_writelane_b32 v249, s9, 8
	v_cmp_gt_u32_e64 s[8:9], s1, v45
	v_or_b32_e32 v45, 2, v44
	v_sub_u32_e32 v46, v42, v45
	v_writelane_b32 v249, s8, 9
	v_cvt_f32_u32_e32 v135, v46
	s_nop 0
	v_writelane_b32 v249, s9, 10
	v_cmp_lt_i32_e64 s[8:9], s5, v44
	v_or_b32_e32 v44, 3, v44
	s_nop 0
	v_writelane_b32 v249, s8, 11
	s_nop 1
	v_writelane_b32 v249, s9, 12
	v_cmp_gt_u32_e64 s[8:9], s1, v46
	s_nop 1
	v_writelane_b32 v249, s8, 13
	s_nop 1
	v_writelane_b32 v249, s9, 14
	v_cmp_lt_i32_e64 s[8:9], s3, v45
	v_sub_u32_e32 v45, v42, v44
	v_cvt_f32_u32_e32 v136, v45
	v_writelane_b32 v249, s8, 15
	s_nop 1
	v_writelane_b32 v249, s9, 16
	v_cmp_gt_u32_e64 s[8:9], s1, v45
	s_nop 1
	v_writelane_b32 v249, s8, 17
	s_nop 1
	v_writelane_b32 v249, s9, 18
	v_cmp_lt_i32_e64 s[8:9], s3, v44
	v_or_b32_e32 v44, s10, v20
	v_sub_u32_e32 v45, v42, v44
	v_writelane_b32 v249, s8, 19
	v_cvt_f32_u32_e32 v137, v45
	s_nop 0
	v_writelane_b32 v249, s9, 20
	v_cmp_gt_u32_e64 s[8:9], s1, v45
	v_xad_u32 v45, v44, -1, v42
	v_cvt_f32_u32_e32 v138, v45
	v_writelane_b32 v249, s8, 21
	s_nop 1
	v_writelane_b32 v249, s9, 22
	v_cmp_lt_i32_e64 s[8:9], s3, v44
	s_nop 1
	v_writelane_b32 v249, s8, 23
	s_nop 1
	v_writelane_b32 v249, s9, 24
	v_cmp_gt_u32_e64 s[8:9], s1, v45
	v_or_b32_e32 v45, 2, v44
	v_sub_u32_e32 v46, v42, v45
	v_writelane_b32 v249, s8, 25
	v_cvt_f32_u32_e32 v139, v46
	s_nop 0
	v_writelane_b32 v249, s9, 26
	v_cmp_lt_i32_e64 s[8:9], s5, v44
	v_or_b32_e32 v44, 3, v44
	s_nop 0
	v_writelane_b32 v249, s8, 27
	s_nop 1
	v_writelane_b32 v249, s9, 28
	v_cmp_gt_u32_e64 s[8:9], s1, v46
	s_nop 1
	v_writelane_b32 v249, s8, 29
	s_nop 1
	v_writelane_b32 v249, s9, 30
	v_cmp_lt_i32_e64 s[8:9], s3, v45
	v_sub_u32_e32 v45, v42, v44
	v_cvt_f32_u32_e32 v140, v45
	v_writelane_b32 v249, s8, 31
	s_nop 1
	v_writelane_b32 v249, s9, 32
	v_cmp_gt_u32_e64 s[8:9], s1, v45
	s_nop 1
	v_writelane_b32 v249, s8, 33
	s_nop 1
	v_writelane_b32 v249, s9, 34
	v_cmp_lt_i32_e64 s[8:9], s3, v44
	v_or_b32_e32 v44, s11, v20
	v_sub_u32_e32 v45, v42, v44
	v_writelane_b32 v249, s8, 35
	v_cvt_f32_u32_e32 v141, v45
	s_mov_b32 s11, s2
	v_writelane_b32 v249, s9, 36
	v_cmp_gt_u32_e64 s[8:9], s1, v45
	v_xad_u32 v45, v44, -1, v42
	v_cvt_f32_u32_e32 v142, v45
	v_writelane_b32 v249, s8, 37
	s_nop 1
	v_writelane_b32 v249, s9, 38
	v_cmp_lt_i32_e64 s[8:9], s3, v44
	s_nop 1
	v_writelane_b32 v249, s8, 39
	s_nop 1
	v_writelane_b32 v249, s9, 40
	v_cmp_gt_u32_e64 s[8:9], s1, v45
	v_or_b32_e32 v45, 2, v44
	v_sub_u32_e32 v46, v42, v45
	v_writelane_b32 v249, s8, 41
	v_cvt_f32_u32_e32 v143, v46
	s_nop 0
	v_writelane_b32 v249, s9, 42
	v_cmp_lt_i32_e64 s[8:9], s5, v44
	v_or_b32_e32 v44, 3, v44
	s_nop 0
	v_writelane_b32 v249, s8, 43
	s_nop 1
	v_writelane_b32 v249, s9, 44
	v_cmp_gt_u32_e64 s[8:9], s1, v46
	s_nop 1
	v_writelane_b32 v249, s8, 45
	s_nop 1
	v_writelane_b32 v249, s9, 46
	v_cmp_lt_i32_e64 s[8:9], s3, v45
	v_sub_u32_e32 v45, v42, v44
	v_cvt_f32_u32_e32 v145, v45
	v_writelane_b32 v249, s8, 47
	s_nop 1
	v_writelane_b32 v249, s9, 48
	v_cmp_gt_u32_e64 s[8:9], s1, v45
	s_nop 1
	v_writelane_b32 v249, s8, 49
	s_nop 1
	v_writelane_b32 v249, s9, 50
	v_cmp_lt_i32_e64 s[8:9], s3, v44
	v_or_b32_e32 v44, s12, v20
	v_sub_u32_e32 v45, v42, v44
	v_writelane_b32 v249, s8, 51
	v_cvt_f32_u32_e32 v146, v45
	s_nop 0
	v_writelane_b32 v249, s9, 52
	v_cmp_gt_u32_e64 s[8:9], s1, v45
	v_xad_u32 v45, v44, -1, v42
	v_cvt_f32_u32_e32 v147, v45
	v_writelane_b32 v249, s8, 53
	s_nop 1
	v_writelane_b32 v249, s9, 54
	v_cmp_lt_i32_e64 s[8:9], s3, v44
	s_nop 1
	v_writelane_b32 v249, s8, 55
	s_nop 1
	v_writelane_b32 v249, s9, 56
	v_cmp_gt_u32_e64 s[8:9], s1, v45
	v_or_b32_e32 v45, 2, v44
	v_sub_u32_e32 v46, v42, v45
	v_writelane_b32 v249, s8, 57
	v_cvt_f32_u32_e32 v148, v46
	s_nop 0
	v_writelane_b32 v249, s9, 58
	v_cmp_lt_i32_e64 s[8:9], s5, v44
	v_or_b32_e32 v44, 3, v44
	s_nop 0
	v_writelane_b32 v249, s8, 59
	s_nop 1
	v_writelane_b32 v249, s9, 60
	v_cmp_gt_u32_e64 s[8:9], s1, v46
	s_nop 1
	v_writelane_b32 v249, s8, 61
	s_nop 1
	v_writelane_b32 v249, s9, 62
	v_cmp_lt_i32_e64 s[8:9], s3, v45
	v_sub_u32_e32 v45, v42, v44
	v_cvt_f32_u32_e32 v149, v45
	v_writelane_b32 v249, s8, 63
	s_nop 1
	v_writelane_b32 v248, s9, 0
	v_cmp_gt_u32_e64 s[8:9], s1, v45
	s_nop 1
	v_writelane_b32 v248, s8, 1
	s_nop 1
	v_writelane_b32 v248, s9, 2
	v_cmp_lt_i32_e64 s[8:9], s3, v44
	v_or_b32_e32 v44, s13, v20
	v_sub_u32_e32 v45, v42, v44
	v_writelane_b32 v248, s8, 3
	v_cvt_f32_u32_e32 v150, v45
	v_cmp_lt_i32_e64 s[16:17], s5, v44
	v_writelane_b32 v248, s9, 4
	v_cmp_gt_u32_e64 s[8:9], s1, v45
	v_xad_u32 v45, v44, -1, v42
	v_cmp_gt_u32_e64 s[14:15], s1, v45
	v_writelane_b32 v248, s8, 5
	v_cvt_f32_u32_e32 v151, v45
	v_or_b32_e32 v45, 2, v44
	v_writelane_b32 v248, s9, 6
	v_cmp_lt_i32_e64 s[8:9], s3, v44
	v_or_b32_e32 v44, 3, v44
	v_sub_u32_e32 v46, v42, v45
	v_cmp_lt_i32_e64 s[20:21], s3, v45
	v_sub_u32_e32 v45, v42, v44
	v_cmp_lt_i32_e64 s[24:25], s3, v44
	v_or_b32_e32 v44, s7, v20
	v_cmp_gt_u32_e64 s[22:23], s1, v45
	v_cvt_f32_u32_e32 v153, v45
	v_sub_u32_e32 v45, v42, v44
	v_cmp_gt_u32_e64 s[26:27], s1, v45
	v_cvt_f32_u32_e32 v154, v45
	v_xad_u32 v45, v44, -1, v42
	v_cmp_lt_i32_e64 s[28:29], s3, v44
; __device__ __forceinline__ void attn_phase(const Params& p, LAS unsigned char* lds, int tid, int G, int bid) {
;     ...
;             for (int j = 0; j < 4; ++j) { const int kj = 16 * (tstart + tt) + 4 * quad + j, delta = qi + 128 - kj;
;                 const bool valid = (delta >= 0) && (delta <= 128) && (nb > 0 || kj >= 128);
;                 const float v = valid ? s[tt][j] - sl2 * (float)delta : -INFINITY; s[tt][j] = v; mx = fmaxf(mx, v); }
	v_cmp_gt_u32_e64 s[30:31], s1, v45
	v_cmp_lt_i32_e64 s[34:35], s5, v44
	v_cvt_f32_u32_e32 v155, v45
	v_or_b32_e32 v45, 2, v44
	v_or_b32_e32 v44, 3, v44
	v_cmp_gt_u32_e64 s[18:19], s1, v46
	v_cvt_f32_u32_e32 v152, v46
	v_sub_u32_e32 v46, v42, v45
	v_cmp_lt_i32_e64 s[38:39], s3, v45
	v_sub_u32_e32 v45, v42, v44
	v_cmp_lt_i32_e64 s[42:43], s3, v44
	v_or_b32_e32 v44, s6, v20
	v_cmp_gt_u32_e64 s[40:41], s1, v45
	v_cvt_f32_u32_e32 v157, v45
	v_sub_u32_e32 v45, v42, v44
	v_cmp_gt_u32_e64 s[44:45], s1, v45
	v_cvt_f32_u32_e32 v158, v45
	v_xad_u32 v45, v44, -1, v42
	v_cmp_lt_i32_e64 s[46:47], s3, v44
	v_cmp_gt_u32_e64 s[48:49], s1, v45
	v_cmp_lt_i32_e64 s[50:51], s5, v44
	v_cvt_f32_u32_e32 v159, v45
	v_or_b32_e32 v45, 2, v44
	v_or_b32_e32 v44, 3, v44
	v_cmp_gt_u32_e64 s[36:37], s1, v46
	v_cvt_f32_u32_e32 v156, v46
	v_sub_u32_e32 v46, v42, v45
	v_cmp_lt_i32_e64 s[54:55], s3, v45
	v_sub_u32_e32 v45, v42, v44
	v_cmp_lt_i32_e64 s[58:59], s3, v44
	v_or_b32_e32 v44, s4, v20
	v_cmp_gt_u32_e64 s[56:57], s1, v45
	v_cvt_f32_u32_e32 v161, v45
	v_sub_u32_e32 v45, v42, v44
	v_cmp_gt_u32_e64 s[60:61], s1, v45
	v_cvt_f32_u32_e32 v162, v45
	v_xad_u32 v45, v44, -1, v42
	v_cmp_lt_i32_e64 s[62:63], s3, v44
	v_cmp_gt_u32_e64 s[64:65], s1, v45
	v_cmp_lt_i32_e64 s[66:67], s5, v44
	v_cvt_f32_u32_e32 v163, v45
	v_or_b32_e32 v45, 2, v44
	v_or_b32_e32 v44, 3, v44
	v_cmp_gt_u32_e64 s[52:53], s1, v46
	v_cvt_f32_u32_e32 v160, v46
	v_sub_u32_e32 v46, v42, v45
	v_cmp_lt_i32_e64 s[70:71], s3, v45
	v_sub_u32_e32 v42, v42, v44
	v_cmp_lt_i32_e64 s[74:75], s3, v44
	s_ashr_i32 s3, s2, 31
	v_cmp_gt_u32_e64 s[68:69], s1, v46
	v_cmp_gt_u32_e64 s[72:73], s1, v42
	v_add_u32_e32 v44, s0, v43
	s_lshl_b64 s[0:1], s[2:3], 9
	s_add_u32 s0, s94, s0
	v_cvt_f32_u32_e32 v164, v46
	v_cvt_f32_u32_e32 v165, v42
	v_lshlrev_b32_e32 v42, 1, v94
	v_mov_b32_e32 v43, v8
	s_addc_u32 s1, s95, s1
	v_lshl_add_u64 v[96:97], s[90:91], 0, v[42:43]
	v_lshl_add_u64 v[42:43], v[92:93], 2, s[0:1]
	s_mov_b64 s[0:1], 0x4000000
	v_add_u32_e32 v20, 0, v24
	v_writelane_b32 v248, s8, 7
	v_lshl_add_u64 v[98:99], v[42:43], 0, s[0:1]
	s_ashr_i32 s1, s98, 31
	s_mov_b32 s0, s98
	v_add_u32_e32 v93, v26, v33
	v_add_u32_e32 v180, v44, v41
	v_add_u32_e32 v183, 0x16800, v20
	v_mov_b64_e32 v[46:47], v[10:11]
	v_mov_b64_e32 v[22:23], v[10:11]
	v_mov_b64_e32 v[42:43], v[10:11]
	v_mov_b64_e32 v[34:35], v[10:11]
	v_mov_b64_e32 v[26:27], v[10:11]
	v_writelane_b32 v248, s9, 8
	s_lshl_b64 s[88:89], s[0:1], 9
	s_mov_b32 s3, 0x41400000
	s_mov_b32 s8, 0
	v_mov_b64_e32 v[44:45], v[8:9]
	v_mov_b64_e32 v[20:21], v[8:9]
	v_mov_b64_e32 v[40:41], v[8:9]
	v_mov_b64_e32 v[32:33], v[8:9]
	v_mov_b64_e32 v[24:25], v[8:9]
	v_mov_b32_e32 v213, 0x7f800000
	v_cmp_lt_f32_e32 vcc, 0x43000000, v125
	v_cndmask_b32_e32 v125, v125, v213, vcc
	v_cmp_lt_f32_e32 vcc, 0x43000000, v126
	v_cndmask_b32_e32 v126, v126, v213, vcc
	v_cmp_lt_f32_e32 vcc, 0x43000000, v127
	v_cndmask_b32_e32 v127, v127, v213, vcc
	v_cmp_lt_f32_e32 vcc, 0x43000000, v128
	v_cndmask_b32_e32 v128, v128, v213, vcc
	v_cmp_lt_f32_e32 vcc, 0x43000000, v129
	v_cndmask_b32_e32 v129, v129, v213, vcc
	v_cmp_lt_f32_e32 vcc, 0x43000000, v130
	v_cndmask_b32_e32 v130, v130, v213, vcc
	v_cmp_lt_f32_e32 vcc, 0x43000000, v131
	v_cndmask_b32_e32 v131, v131, v213, vcc
	v_cmp_lt_f32_e32 vcc, 0x43000000, v132
	v_cndmask_b32_e32 v132, v132, v213, vcc
	v_cmp_lt_f32_e32 vcc, 0x43000000, v133
	v_cndmask_b32_e32 v133, v133, v213, vcc
	v_cmp_lt_f32_e32 vcc, 0x43000000, v134
	v_cndmask_b32_e32 v134, v134, v213, vcc
	v_cmp_lt_f32_e32 vcc, 0x43000000, v135
	v_cndmask_b32_e32 v135, v135, v213, vcc
	v_cmp_lt_f32_e32 vcc, 0x43000000, v136
	v_cndmask_b32_e32 v136, v136, v213, vcc
	v_cmp_lt_f32_e32 vcc, 0x43000000, v137
	v_cndmask_b32_e32 v137, v137, v213, vcc
	v_cmp_lt_f32_e32 vcc, 0x43000000, v138
	v_cndmask_b32_e32 v138, v138, v213, vcc
	v_cmp_lt_f32_e32 vcc, 0x43000000, v139
	v_cndmask_b32_e32 v139, v139, v213, vcc
	v_cmp_lt_f32_e32 vcc, 0x43000000, v140
	v_cndmask_b32_e32 v140, v140, v213, vcc
	v_cmp_lt_f32_e32 vcc, 0x43000000, v141
	v_cndmask_b32_e32 v141, v141, v213, vcc
	v_cmp_lt_f32_e32 vcc, 0x43000000, v142
	v_cndmask_b32_e32 v142, v142, v213, vcc
	v_cmp_lt_f32_e32 vcc, 0x43000000, v143
	v_cndmask_b32_e32 v143, v143, v213, vcc
	v_cmp_lt_f32_e32 vcc, 0x43000000, v145
	v_cndmask_b32_e32 v145, v145, v213, vcc
	v_cmp_lt_f32_e32 vcc, 0x43000000, v146
	v_cndmask_b32_e32 v146, v146, v213, vcc
	v_cmp_lt_f32_e32 vcc, 0x43000000, v147
	v_cndmask_b32_e32 v147, v147, v213, vcc
	v_cmp_lt_f32_e32 vcc, 0x43000000, v148
	v_cndmask_b32_e32 v148, v148, v213, vcc
	v_cmp_lt_f32_e32 vcc, 0x43000000, v149
	v_cndmask_b32_e32 v149, v149, v213, vcc
	v_cmp_lt_f32_e32 vcc, 0x43000000, v150
	v_cndmask_b32_e32 v150, v150, v213, vcc
	v_cmp_lt_f32_e32 vcc, 0x43000000, v151
	v_cndmask_b32_e32 v151, v151, v213, vcc
	v_cmp_lt_f32_e32 vcc, 0x43000000, v152
	v_cndmask_b32_e32 v152, v152, v213, vcc
	v_cmp_lt_f32_e32 vcc, 0x43000000, v153
	v_cndmask_b32_e32 v153, v153, v213, vcc
	v_cmp_lt_f32_e32 vcc, 0x43000000, v154
	v_cndmask_b32_e32 v154, v154, v213, vcc
	v_cmp_lt_f32_e32 vcc, 0x43000000, v155
	v_cndmask_b32_e32 v155, v155, v213, vcc
	v_cmp_lt_f32_e32 vcc, 0x43000000, v156
	v_cndmask_b32_e32 v156, v156, v213, vcc
	v_cmp_lt_f32_e32 vcc, 0x43000000, v157
	v_cndmask_b32_e32 v157, v157, v213, vcc
	v_cmp_lt_f32_e32 vcc, 0x43000000, v158
	v_cndmask_b32_e32 v158, v158, v213, vcc
	v_cmp_lt_f32_e32 vcc, 0x43000000, v159
	v_cndmask_b32_e32 v159, v159, v213, vcc
	v_cmp_lt_f32_e32 vcc, 0x43000000, v160
	v_cndmask_b32_e32 v160, v160, v213, vcc
	v_cmp_lt_f32_e32 vcc, 0x43000000, v161
	v_cndmask_b32_e32 v161, v161, v213, vcc
	v_cmp_lt_f32_e32 vcc, 0x43000000, v162
	v_cndmask_b32_e32 v162, v162, v213, vcc
	v_cmp_lt_f32_e32 vcc, 0x43000000, v163
	v_cndmask_b32_e32 v163, v163, v213, vcc
	v_cmp_lt_f32_e32 vcc, 0x43000000, v164
	v_cndmask_b32_e32 v164, v164, v213, vcc
	v_cmp_lt_f32_e32 vcc, 0x43000000, v165
	v_cndmask_b32_e32 v165, v165, v213, vcc
	s_mov_b32 s9, 0
	s_branch .LBB0_271

; #define LAS __attribute__((address_space(3)))
; __device__ __forceinline__ void attn_phase(const Params& p, LAS unsigned char* lds, int tid, int G, int bid) {
;     ...
;         for (int tt = 0; tt < 10; ++tt) { const LAS unsigned char* kp = lds + (16 * (tstart + tt) + fr) * KS_PITCH + quad * 8;
;             const long k0 = *(const LAS long*)kp, k1 = *(const LAS long*)(kp + 32);
;             f32x4 a = {0.f, 0.f, 0.f, 0.f};
;             a = __builtin_amdgcn_mfma_f32_16x16x32_fp8_fp8(k0, q0, a, 0, 0, 0);
;             s[tt] = __builtin_amdgcn_mfma_f32_16x16x32_fp8_fp8(k1, q1, a, 0, 0, 0) * C2; }
;         const float sl2 = __builtin_amdgcn_exp2f(-8.0f * (float)(head + 1) / 12.0f) * (float)d * LOG2E;
;         float mx = -INFINITY;
; #pragma unroll
;         for (int tt = 0; tt < 10; ++tt)
; #pragma unroll
;             for (int j = 0; j < 4; ++j) { const int kj = 16 * (tstart + tt) + 4 * quad + j, delta = qi + 128 - kj;
;                 const bool valid = (delta >= 0) && (delta <= 128) && (nb > 0 || kj >= 128);
;                 const float v = valid ? s[tt][j] - sl2 * (float)delta : -INFINITY; s[tt][j] = v; mx = fmaxf(mx, v); }
.LBB0_284:
	ds_read2_b64 v[64:67], v169 offset1:4
	s_mul_hi_i32 s0, s11, 0x2aaaaaab
	s_lshr_b32 s1, s0, 31
	s_ashr_i32 s0, s0, 5
	s_add_i32 s0, s0, s1
	s_mul_i32 s1, s0, 0xffffff40
	s_add_i32 s1, s11, s1
	s_ashr_i32 s4, s1, 6
	s_and_b32 s6, s11, 15
	s_waitcnt lgkmcnt(0)
	v_mfma_f32_16x16x32_fp8_fp8 v[68:71], v[64:65], v[62:63], 0
	s_lshl_b32 s7, s4, 2
	s_bfe_u32 s11, s11, 0x20004
	s_or_b32 s7, s11, s7
	v_mfma_f32_16x16x32_fp8_fp8 v[64:67], v[66:67], v[60:61], v[68:71]
	s_add_i32 s7, s7, 1
	v_cvt_f32_i32_e32 v9, s7
	s_lshl_b32 s1, s4, 1
	s_lshl_b32 s5, -1, s1
	s_andn2_b32 s5, s6, s5
	s_nop 2
	v_pk_mul_f32 v[116:117], v[66:67], s[80:81] op_sel_hi:[1,0]
	v_pk_mul_f32 v[118:119], v[64:65], s[80:81] op_sel_hi:[1,0]
	ds_read2_b64 v[64:67], v171 offset1:4
	v_mul_f32_e32 v9, 0xc1000000, v9
	s_lshr_b32 s86, s6, s1
	s_lshl_b32 s6, 1, s1
	s_cmp_lg_u32 s86, 0
	s_waitcnt lgkmcnt(0)
	v_mfma_f32_16x16x32_fp8_fp8 v[68:71], v[64:65], v[62:63], 0
	v_readlane_b32 s12, v250, 39
	v_readlane_b32 s13, v250, 40
	v_mfma_f32_16x16x32_fp8_fp8 v[64:67], v[66:67], v[60:61], v[68:71]
	s_nop 7
	v_pk_mul_f32 v[112:113], v[66:67], s[80:81] op_sel_hi:[1,0]
	v_pk_mul_f32 v[114:115], v[64:65], s[80:81] op_sel_hi:[1,0]
	ds_read2_b64 v[64:67], v172 offset1:4
	s_waitcnt lgkmcnt(0)
	v_mfma_f32_16x16x32_fp8_fp8 v[68:71], v[64:65], v[62:63], 0
	v_mfma_f32_16x16x32_fp8_fp8 v[64:67], v[66:67], v[60:61], v[68:71]
	s_nop 7
	v_pk_mul_f32 v[108:109], v[66:67], s[80:81] op_sel_hi:[1,0]
	v_pk_mul_f32 v[110:111], v[64:65], s[80:81] op_sel_hi:[1,0]
	ds_read2_b64 v[64:67], v173 offset1:4
	s_waitcnt lgkmcnt(0)
	v_mfma_f32_16x16x32_fp8_fp8 v[68:71], v[64:65], v[62:63], 0
	v_mfma_f32_16x16x32_fp8_fp8 v[64:67], v[66:67], v[60:61], v[68:71]
	s_nop 7
	v_pk_mul_f32 v[104:105], v[66:67], s[80:81] op_sel_hi:[1,0]
	v_pk_mul_f32 v[106:107], v[64:65], s[80:81] op_sel_hi:[1,0]
	ds_read2_b64 v[64:67], v174 offset1:4
	s_waitcnt lgkmcnt(0)
	v_mfma_f32_16x16x32_fp8_fp8 v[68:71], v[64:65], v[62:63], 0
	v_mfma_f32_16x16x32_fp8_fp8 v[64:67], v[66:67], v[60:61], v[68:71]
	s_nop 7
	v_pk_mul_f32 v[80:81], v[66:67], s[80:81] op_sel_hi:[1,0]
	v_pk_mul_f32 v[82:83], v[64:65], s[80:81] op_sel_hi:[1,0]
	ds_read2_b64 v[64:67], v175 offset1:4
	s_waitcnt lgkmcnt(0)
	v_mfma_f32_16x16x32_fp8_fp8 v[68:71], v[64:65], v[62:63], 0
	v_mfma_f32_16x16x32_fp8_fp8 v[64:67], v[66:67], v[60:61], v[68:71]
	s_nop 7
	v_pk_mul_f32 v[76:77], v[66:67], s[80:81] op_sel_hi:[1,0]
	v_pk_mul_f32 v[78:79], v[64:65], s[80:81] op_sel_hi:[1,0]
	ds_read2_b64 v[64:67], v176 offset1:4
	s_waitcnt lgkmcnt(0)
	v_mfma_f32_16x16x32_fp8_fp8 v[68:71], v[64:65], v[62:63], 0
	v_mfma_f32_16x16x32_fp8_fp8 v[64:67], v[66:67], v[60:61], v[68:71]
	s_nop 7
	v_pk_mul_f32 v[72:73], v[66:67], s[80:81] op_sel_hi:[1,0]
	v_pk_mul_f32 v[74:75], v[64:65], s[80:81] op_sel_hi:[1,0]
	ds_read2_b64 v[64:67], v177 offset1:4
	s_waitcnt lgkmcnt(0)
	v_mfma_f32_16x16x32_fp8_fp8 v[68:71], v[64:65], v[62:63], 0
	v_mfma_f32_16x16x32_fp8_fp8 v[64:67], v[66:67], v[60:61], v[68:71]
	s_nop 7
	v_pk_mul_f32 v[68:69], v[66:67], s[80:81] op_sel_hi:[1,0]
	v_pk_mul_f32 v[70:71], v[64:65], s[80:81] op_sel_hi:[1,0]
	ds_read2_b64 v[64:67], v178 offset1:4
	s_waitcnt lgkmcnt(0)
	v_mfma_f32_16x16x32_fp8_fp8 v[186:189], v[64:65], v[62:63], 0
	v_mfma_f32_16x16x32_fp8_fp8 v[186:189], v[66:67], v[60:61], v[186:189]
	s_nop 7
	v_pk_mul_f32 v[64:65], v[188:189], s[80:81] op_sel_hi:[1,0]
	v_pk_mul_f32 v[66:67], v[186:187], s[80:81] op_sel_hi:[1,0]
	ds_read2_b64 v[186:189], v179 offset1:4
	s_waitcnt lgkmcnt(0)
	v_mfma_f32_16x16x32_fp8_fp8 v[190:193], v[186:187], v[62:63], 0
	v_mfma_f32_16x16x32_fp8_fp8 v[60:63], v[188:189], v[60:61], v[190:193]
	s_nop 7
	v_pk_mul_f32 v[10:11], v[62:63], s[80:81] op_sel_hi:[1,0]
	v_div_scale_f32 v62, vcc, s3, s3, v9
	v_rcp_f32_e32 v63, v62
	v_pk_mul_f32 v[60:61], v[60:61], s[80:81] op_sel_hi:[1,0]
	v_fma_f32 v186, -v62, v63, 1.0
	v_fmac_f32_e32 v63, v186, v63
	v_div_scale_f32 v186, vcc, v9, s3, v9
	v_mul_f32_e32 v187, v186, v63
	v_fma_f32 v188, -v62, v187, v186
	v_fmac_f32_e32 v187, v188, v63
	v_fma_f32 v62, -v62, v187, v186
	v_div_fmas_f32 v62, v62, v63, v187
	v_div_fixup_f32 v9, v62, s3, v9
	v_exp_f32_e32 v9, v9
	v_cvt_f32_u32_e32 v62, s6
	s_cselect_b64 s[6:7], -1, 0
	v_mul_f32_e32 v9, v9, v62
	v_mul_f32_e32 v9, 0xbfb8aa3b, v9
	v_fma_f32 v62, v9, v125, v118
	v_fma_f32 v63, v9, v126, v119
	v_fmac_f32_e32 v116, v9, v127
	v_fmac_f32_e32 v117, v9, v128
	v_fmac_f32_e32 v114, v9, v129
	v_fmac_f32_e32 v115, v9, v130
	v_fmac_f32_e32 v112, v9, v131
	v_fmac_f32_e32 v113, v9, v132
	v_fmac_f32_e32 v110, v9, v133
	v_fmac_f32_e32 v111, v9, v134
	v_fmac_f32_e32 v108, v9, v135
	v_fmac_f32_e32 v109, v9, v136
	v_fmac_f32_e32 v106, v9, v137
	v_fmac_f32_e32 v107, v9, v138
	v_fmac_f32_e32 v104, v9, v139
	v_fmac_f32_e32 v105, v9, v140
	v_fmac_f32_e32 v82, v9, v141
	v_fmac_f32_e32 v83, v9, v142
	v_fmac_f32_e32 v80, v9, v143
	v_fmac_f32_e32 v81, v9, v145
	v_fmac_f32_e32 v78, v9, v146
	v_fmac_f32_e32 v79, v9, v147
	v_fmac_f32_e32 v76, v9, v148
	v_fmac_f32_e32 v77, v9, v149
	v_fmac_f32_e32 v74, v9, v150
	v_fmac_f32_e32 v75, v9, v151
	v_fmac_f32_e32 v72, v9, v152
	v_fmac_f32_e32 v73, v9, v153
	v_fmac_f32_e32 v70, v9, v154
	v_fmac_f32_e32 v71, v9, v155
	v_fmac_f32_e32 v68, v9, v156
	v_fmac_f32_e32 v69, v9, v157
	v_fmac_f32_e32 v66, v9, v158
	v_fmac_f32_e32 v67, v9, v159
	v_fmac_f32_e32 v64, v9, v160
	v_fmac_f32_e32 v65, v9, v161
	v_fmac_f32_e32 v60, v9, v162
	v_fmac_f32_e32 v61, v9, v163
	v_fmac_f32_e32 v10, v9, v164
	v_fmac_f32_e32 v11, v9, v165
	s_cmp_lg_u32 s6, 0
	s_cbranch_scc1 .Lattn_nb_ok
	v_readfirstlane_b32 s100, v170
	s_lshr_b32 s100, s100, 6
	s_and_b32 s100, s100, 6
	s_sub_i32 s100, 8, s100
	v_mov_b32_e32 v62, v184
	v_mov_b32_e32 v63, v184
	v_mov_b32_e32 v116, v184
	v_mov_b32_e32 v117, v184
	v_mov_b32_e32 v114, v184
	v_mov_b32_e32 v115, v184
	v_mov_b32_e32 v112, v184
	v_mov_b32_e32 v113, v184
	s_cmp_lt_u32 s100, 3
	s_cbranch_scc1 .Lattn_nb_ok
	v_mov_b32_e32 v110, v184
	v_mov_b32_e32 v111, v184
	v_mov_b32_e32 v108, v184
	v_mov_b32_e32 v109, v184
	v_mov_b32_e32 v106, v184
	v_mov_b32_e32 v107, v184
	v_mov_b32_e32 v104, v184
	v_mov_b32_e32 v105, v184
	s_cmp_lt_u32 s100, 5
	s_cbranch_scc1 .Lattn_nb_ok
	v_mov_b32_e32 v82, v184
	v_mov_b32_e32 v83, v184
	v_mov_b32_e32 v80, v184
	v_mov_b32_e32 v81, v184
	v_mov_b32_e32 v78, v184
	v_mov_b32_e32 v79, v184
	v_mov_b32_e32 v76, v184
	v_mov_b32_e32 v77, v184
	s_cmp_lt_u32 s100, 7
	s_cbranch_scc1 .Lattn_nb_ok
	v_mov_b32_e32 v74, v184
	v_mov_b32_e32 v75, v184
	v_mov_b32_e32 v72, v184
	v_mov_b32_e32 v73, v184
	v_mov_b32_e32 v70, v184
	v_mov_b32_e32 v71, v184
	v_mov_b32_e32 v68, v184
	v_mov_b32_e32 v69, v184
; #define LAS __attribute__((address_space(3)))
; __device__ __forceinline__ void attn_phase(const Params& p, LAS unsigned char* lds, int tid, int G, int bid) {
;     ...
;         float mx = -INFINITY;
; #pragma unroll
;         for (int tt = 0; tt < 10; ++tt)
; #pragma unroll
;             for (int j = 0; j < 4; ++j) { const int kj = 16 * (tstart + tt) + 4 * quad + j, delta = qi + 128 - kj;
;                 const bool valid = (delta >= 0) && (delta <= 128) && (nb > 0 || kj >= 128);
;                 const float v = valid ? s[tt][j] - sl2 * (float)delta : -INFINITY; s[tt][j] = v; mx = fmaxf(mx, v); }
;         mx = fmaxf(mx, __shfl_xor(mx, 16)); mx = fmaxf(mx, __shfl_xor(mx, 32));
;         float den = 0.f;
; #pragma unroll
;         for (int tt = 0; tt < 10; ++tt)
; #pragma unroll
;             for (int j = 0; j < 4; ++j) { const float e = __builtin_amdgcn_exp2f(s[tt][j] - mx); s[tt][j] = e; den += e; }
;         den += __shfl_xor(den, 16); den += __shfl_xor(den, 32);
;         f32x4 o[4];
; #pragma unroll
;         for (int dt = 0; dt < 4; ++dt) o[dt] = (f32x4){0.f, 0.f, 0.f, 0.f};
; #pragma unroll
;         for (int c = 0; c < 5; ++c) {
;             int p0_ = 0, p1_ = 0;
;             p0_ = __builtin_amdgcn_cvt_pk_fp8_f32(s[2 * c][0], s[2 * c][1], p0_, false); p0_ = __builtin_amdgcn_cvt_pk_fp8_f32(s[2 * c][2], s[2 * c][3], p0_, true);
;             p1_ = __builtin_amdgcn_cvt_pk_fp8_f32(s[2 * c + 1][0], s[2 * c + 1][1], p1_, false); p1_ = __builtin_amdgcn_cvt_pk_fp8_f32(s[2 * c + 1][2], s[2 * c + 1][3], p1_, true);
;             const long pf = (long)(((unsigned long long)(unsigned)p1_ << 32) | (unsigned long long)(unsigned)p0_);
; #pragma unroll
;             for (int dt = 0; dt < 4; ++dt) { const LAS unsigned char* vp = lds + VT_OFF + (16 * dt + fr) * VT_PITCH + 16 * (tstart + 2 * c) + 4 * quad;
;                 const unsigned lo = *(const LAS unsigned*)vp, hi = *(const LAS unsigned*)(vp + 16);
;                 const long vf = (long)(((unsigned long long)hi << 32) | (unsigned long long)lo);
;                 o[dt] = __builtin_amdgcn_mfma_f32_16x16x32_fp8_fp8(vf, pf, o[dt], 0, 0, 0); }
.Lattn_nb_ok:
	s_mov_b32 s12, 0xff800000
	v_max3_f32 v118, v62, s12, v63
	v_max3_f32 v118, v118, v116, v117
	v_max3_f32 v118, v118, v114, v115
	v_max3_f32 v118, v118, v112, v113
	v_max3_f32 v118, v118, v110, v111
	v_max3_f32 v118, v118, v108, v109
	v_max3_f32 v118, v118, v106, v107
	v_max3_f32 v118, v118, v104, v105
	v_max3_f32 v118, v118, v82, v83
	v_max3_f32 v118, v118, v80, v81
	v_max3_f32 v118, v118, v78, v79
	v_max3_f32 v118, v118, v76, v77
	v_max3_f32 v118, v118, v74, v75
	v_max3_f32 v118, v118, v72, v73
	v_max3_f32 v118, v118, v70, v71
	v_max3_f32 v118, v118, v68, v69
	v_max3_f32 v118, v118, v66, v67
	v_max3_f32 v118, v118, v64, v65
	v_max3_f32 v118, v118, v60, v61
	v_max3_f32 v9, v118, v10, v11
	ds_bpermute_b32 v118, v122, v9
	s_waitcnt lgkmcnt(0)
	v_max_f32_e32 v118, v118, v118
	v_max_f32_e32 v9, v9, v118
	ds_bpermute_b32 v118, v123, v9
	s_waitcnt lgkmcnt(0)
	v_max_f32_e32 v118, v118, v118
	v_max_f32_e32 v9, v9, v118
	v_sub_f32_e32 v62, v62, v9
	v_exp_f32_e32 v62, v62
	v_sub_f32_e32 v63, v63, v9
	v_exp_f32_e32 v63, v63
	v_sub_f32_e32 v116, v116, v9
	v_exp_f32_e32 v116, v116
	v_sub_f32_e32 v117, v117, v9
	v_exp_f32_e32 v117, v117
	v_sub_f32_e32 v114, v114, v9
	v_add_f32_e32 v118, 0, v62
	v_exp_f32_e32 v114, v114
	v_sub_f32_e32 v115, v115, v9
	v_add_f32_e32 v118, v63, v118
	v_exp_f32_e32 v115, v115
	v_sub_f32_e32 v112, v112, v9
	v_add_f32_e32 v118, v116, v118
	v_exp_f32_e32 v112, v112
	v_sub_f32_e32 v113, v113, v9
	v_add_f32_e32 v118, v117, v118
	v_exp_f32_e32 v113, v113
	v_sub_f32_e32 v110, v110, v9
	v_add_f32_e32 v118, v114, v118
	v_exp_f32_e32 v110, v110
	v_sub_f32_e32 v111, v111, v9
	v_add_f32_e32 v118, v115, v118
	v_exp_f32_e32 v111, v111
	v_sub_f32_e32 v108, v108, v9
	v_add_f32_e32 v118, v112, v118
	v_exp_f32_e32 v108, v108
	v_sub_f32_e32 v109, v109, v9
	v_add_f32_e32 v118, v113, v118
	v_exp_f32_e32 v109, v109
	v_sub_f32_e32 v106, v106, v9
	v_add_f32_e32 v118, v110, v118
	v_exp_f32_e32 v106, v106
	v_sub_f32_e32 v107, v107, v9
	v_add_f32_e32 v118, v111, v118
	v_exp_f32_e32 v107, v107
	v_sub_f32_e32 v104, v104, v9
	v_add_f32_e32 v118, v108, v118
	v_exp_f32_e32 v104, v104
	v_sub_f32_e32 v105, v105, v9
	v_add_f32_e32 v118, v109, v118
	v_exp_f32_e32 v105, v105
	v_sub_f32_e32 v82, v82, v9
	v_add_f32_e32 v118, v106, v118
	v_exp_f32_e32 v82, v82
	v_sub_f32_e32 v83, v83, v9
	v_add_f32_e32 v118, v107, v118
	v_exp_f32_e32 v83, v83
	v_sub_f32_e32 v80, v80, v9
	v_add_f32_e32 v118, v104, v118
	v_exp_f32_e32 v80, v80
	v_sub_f32_e32 v81, v81, v9
	v_add_f32_e32 v118, v105, v118
	v_exp_f32_e32 v81, v81
	v_sub_f32_e32 v78, v78, v9
	v_add_f32_e32 v118, v82, v118
	v_exp_f32_e32 v78, v78
	v_sub_f32_e32 v79, v79, v9
	v_add_f32_e32 v118, v83, v118
	v_exp_f32_e32 v79, v79
	v_sub_f32_e32 v76, v76, v9
	v_add_f32_e32 v118, v80, v118
	v_exp_f32_e32 v119, v76
	v_add_f32_e32 v118, v81, v118
	v_add_f32_e32 v118, v78, v118
	v_add_f32_e32 v118, v79, v118
	v_sub_f32_e32 v77, v77, v9
	v_add_f32_e32 v76, v119, v118
	v_exp_f32_e32 v118, v77
	v_sub_f32_e32 v74, v74, v9
	v_exp_f32_e32 v186, v74
	v_sub_f32_e32 v75, v75, v9
	v_exp_f32_e32 v187, v75
	v_sub_f32_e32 v72, v72, v9
	v_exp_f32_e32 v188, v72
	v_sub_f32_e32 v73, v73, v9
	v_add_f32_e32 v76, v118, v76
	v_exp_f32_e32 v189, v73
	v_sub_f32_e32 v70, v70, v9
	v_add_f32_e32 v74, v186, v76
	v_exp_f32_e32 v190, v70
	v_sub_f32_e32 v71, v71, v9
	v_add_f32_e32 v74, v187, v74
	v_exp_f32_e32 v191, v71
	v_sub_f32_e32 v68, v68, v9
	v_add_f32_e32 v72, v188, v74
	v_exp_f32_e32 v192, v68
	v_sub_f32_e32 v69, v69, v9
	v_add_f32_e32 v72, v189, v72
	v_exp_f32_e32 v193, v69
	v_sub_f32_e32 v66, v66, v9
	v_add_f32_e32 v70, v190, v72
	v_exp_f32_e32 v194, v66
	v_sub_f32_e32 v67, v67, v9
	v_add_f32_e32 v70, v191, v70
	v_exp_f32_e32 v195, v67
	v_sub_f32_e32 v64, v64, v9
	v_add_f32_e32 v68, v192, v70
	v_exp_f32_e32 v196, v64
	v_sub_f32_e32 v65, v65, v9
	v_add_f32_e32 v68, v193, v68
	v_exp_f32_e32 v197, v65
	v_sub_f32_e32 v60, v60, v9
	v_add_f32_e32 v66, v194, v68
	v_exp_f32_e32 v198, v60
	v_sub_f32_e32 v61, v61, v9
	v_add_f32_e32 v66, v195, v66
	v_exp_f32_e32 v199, v61
	v_sub_f32_e32 v10, v10, v9
	v_add_f32_e32 v64, v196, v66
	v_exp_f32_e32 v200, v10
	v_sub_f32_e32 v11, v11, v9
	v_add_f32_e32 v64, v197, v64
	v_exp_f32_e32 v201, v11
	v_add_f32_e32 v60, v198, v64
	v_add_f32_e32 v60, v199, v60
	v_add_f32_e32 v10, v200, v60
	v_add_f32_e32 v10, v201, v10
	ds_bpermute_b32 v11, v122, v10
	s_waitcnt lgkmcnt(0)
	v_add_f32_e32 v202, v10, v11
	v_mov_b32_e32 v11, v8
	v_cvt_pk_fp8_f32 v11, v114, v115
	v_add_u32_e32 v114, 0x7000, v180
	v_add_u32_e32 v115, 0x8000, v180
	v_mov_b32_e32 v10, v8
	v_cvt_pk_fp8_f32 v11, v112, v113 op_sel:[0,0,1]
	v_add_u32_e32 v112, 0x5000, v180
	v_add_u32_e32 v113, 0x6000, v180
	ds_read2_b32 v[60:61], v112 offset1:4
	ds_read2_b32 v[76:77], v112 offset0:8 offset1:12
	ds_read2_b32 v[64:65], v113 offset0:64 offset1:68
	ds_read2_b32 v[68:69], v114 offset0:128 offset1:132
	ds_read2_b32 v[72:73], v115 offset0:192 offset1:196
	v_cvt_pk_fp8_f32 v10, v62, v63
	ds_bpermute_b32 v203, v123, v202
	v_cvt_pk_fp8_f32 v10, v116, v117 op_sel:[0,0,1]
	s_waitcnt lgkmcnt(5)
	s_nop 0
	v_mfma_f32_16x16x32_fp8_fp8 v[60:63], v[60:61], v[10:11], 0
	s_waitcnt lgkmcnt(3)
	v_mfma_f32_16x16x32_fp8_fp8 v[64:67], v[64:65], v[10:11], 0
	s_waitcnt lgkmcnt(2)
	v_mfma_f32_16x16x32_fp8_fp8 v[68:71], v[68:69], v[10:11], 0
	s_waitcnt lgkmcnt(1)
	v_mfma_f32_16x16x32_fp8_fp8 v[72:75], v[72:73], v[10:11], 0
	v_mov_b32_e32 v10, v8
	v_mov_b32_e32 v11, v8
	v_cvt_pk_fp8_f32 v10, v110, v111
	v_cvt_pk_fp8_f32 v11, v106, v107
	v_cvt_pk_fp8_f32 v10, v108, v109 op_sel:[0,0,1]
	v_cvt_pk_fp8_f32 v11, v104, v105 op_sel:[0,0,1]
	s_nop 1
	v_mfma_f32_16x16x32_fp8_fp8 v[60:63], v[76:77], v[10:11], v[60:63]
	ds_read2_b32 v[76:77], v113 offset0:72 offset1:76
	s_waitcnt lgkmcnt(0)
; #define LAS __attribute__((address_space(3)))
; __device__ __forceinline__ float f8c(float v) { return fminf(fmaxf(v, -448.f), 448.f); }
; #define LDS_WAIT() asm volatile("s_waitcnt lgkmcnt(0)" ::: "memory")
; __device__ __forceinline__ void attn_phase(const Params& p, LAS unsigned char* lds, int tid, int G, int bid) {
;     ...
;         for (int c = 0; c < 5; ++c) {
;             int p0_ = 0, p1_ = 0;
;             p0_ = __builtin_amdgcn_cvt_pk_fp8_f32(s[2 * c][0], s[2 * c][1], p0_, false); p0_ = __builtin_amdgcn_cvt_pk_fp8_f32(s[2 * c][2], s[2 * c][3], p0_, true);
;             p1_ = __builtin_amdgcn_cvt_pk_fp8_f32(s[2 * c + 1][0], s[2 * c + 1][1], p1_, false); p1_ = __builtin_amdgcn_cvt_pk_fp8_f32(s[2 * c + 1][2], s[2 * c + 1][3], p1_, true);
;             const long pf = (long)(((unsigned long long)(unsigned)p1_ << 32) | (unsigned long long)(unsigned)p0_);
; #pragma unroll
;             for (int dt = 0; dt < 4; ++dt) { const LAS unsigned char* vp = lds + VT_OFF + (16 * dt + fr) * VT_PITCH + 16 * (tstart + 2 * c) + 4 * quad;
;                 const unsigned lo = *(const LAS unsigned*)vp, hi = *(const LAS unsigned*)(vp + 16);
;                 const long vf = (long)(((unsigned long long)hi << 32) | (unsigned long long)lo);
;                 o[dt] = __builtin_amdgcn_mfma_f32_16x16x32_fp8_fp8(vf, pf, o[dt], 0, 0, 0); }
;         }
;         const float inv = 1.0f / den;
;         { LAS unsigned char* ost = lds + OST_OFF + w * 2304;
; #pragma unroll
;           for (int dt = 0; dt < 4; ++dt) { int wv = 0; wv = __builtin_amdgcn_cvt_pk_fp8_f32(f8c(o[dt][0] * inv), f8c(o[dt][1] * inv), wv, false); wv = __builtin_amdgcn_cvt_pk_fp8_f32(f8c(o[dt][2] * inv), f8c(o[dt][3] * inv), wv, true);
;               *(LAS unsigned*)(ost + fr * 80 + 16 * dt + 4 * quad) = (unsigned)wv; }
;           LDS_WAIT();
;           const int q2 = lane >> 2, ck = lane & 3, tq2 = ((nb * 128 + 16 * w + q2) << dsh) + r;
;           const u32x4 r0 = *(const LAS u32x4*)(ost + q2 * 80 + ck * 16);
;           unsigned char* op = (unsigned char*)OG + ((size_t)g * M + (size_t)b * SEQ + tq2) * AOW + hh * 64 + ck * 16;
;           *(u32x4*)op = r0; }
;         if (quad == 0) LSE[(size_t)uid * 128 + qi] = (mx + __builtin_amdgcn_logf(den)) * LN2F;
	v_mfma_f32_16x16x32_fp8_fp8 v[64:67], v[76:77], v[10:11], v[64:67]
	ds_read2_b32 v[76:77], v114 offset0:136 offset1:140
	s_waitcnt lgkmcnt(0)
	v_mfma_f32_16x16x32_fp8_fp8 v[68:71], v[76:77], v[10:11], v[68:71]
	ds_read2_b32 v[76:77], v115 offset0:200 offset1:204
	s_waitcnt lgkmcnt(0)
	v_mfma_f32_16x16x32_fp8_fp8 v[72:75], v[76:77], v[10:11], v[72:75]
	v_mov_b32_e32 v10, v8
	v_mov_b32_e32 v11, v8
	ds_read2_b32 v[76:77], v112 offset0:16 offset1:20
	v_cvt_pk_fp8_f32 v10, v82, v83
	v_cvt_pk_fp8_f32 v11, v78, v79
	v_cvt_pk_fp8_f32 v10, v80, v81 op_sel:[0,0,1]
	v_cvt_pk_fp8_f32 v11, v119, v118 op_sel:[0,0,1]
	s_waitcnt lgkmcnt(0)
	s_nop 0
	v_mfma_f32_16x16x32_fp8_fp8 v[60:63], v[76:77], v[10:11], v[60:63]
	ds_read2_b32 v[76:77], v113 offset0:80 offset1:84
	s_waitcnt lgkmcnt(0)
	v_mfma_f32_16x16x32_fp8_fp8 v[64:67], v[76:77], v[10:11], v[64:67]
	ds_read2_b32 v[76:77], v114 offset0:144 offset1:148
	s_waitcnt lgkmcnt(0)
	v_mfma_f32_16x16x32_fp8_fp8 v[68:71], v[76:77], v[10:11], v[68:71]
	ds_read2_b32 v[76:77], v115 offset0:208 offset1:212
	s_waitcnt lgkmcnt(0)
	v_mfma_f32_16x16x32_fp8_fp8 v[72:75], v[76:77], v[10:11], v[72:75]
	v_mov_b32_e32 v10, v8
	v_mov_b32_e32 v11, v8
	ds_read2_b32 v[76:77], v112 offset0:24 offset1:28
	v_cvt_pk_fp8_f32 v10, v186, v187
	v_cvt_pk_fp8_f32 v11, v190, v191
	v_cvt_pk_fp8_f32 v10, v188, v189 op_sel:[0,0,1]
	v_cvt_pk_fp8_f32 v11, v192, v193 op_sel:[0,0,1]
	s_waitcnt lgkmcnt(0)
	s_nop 0
	v_mfma_f32_16x16x32_fp8_fp8 v[60:63], v[76:77], v[10:11], v[60:63]
	ds_read2_b32 v[76:77], v113 offset0:88 offset1:92
	s_waitcnt lgkmcnt(0)
	v_mfma_f32_16x16x32_fp8_fp8 v[64:67], v[76:77], v[10:11], v[64:67]
	ds_read2_b32 v[76:77], v114 offset0:152 offset1:156
	s_waitcnt lgkmcnt(0)
	v_mfma_f32_16x16x32_fp8_fp8 v[68:71], v[76:77], v[10:11], v[68:71]
	ds_read2_b32 v[76:77], v115 offset0:216 offset1:220
	s_waitcnt lgkmcnt(0)
	v_mfma_f32_16x16x32_fp8_fp8 v[72:75], v[76:77], v[10:11], v[72:75]
	v_mov_b32_e32 v10, v8
	v_mov_b32_e32 v11, v8
	ds_read2_b32 v[76:77], v112 offset0:32 offset1:36
	v_cvt_pk_fp8_f32 v10, v194, v195
	v_cvt_pk_fp8_f32 v11, v198, v199
	v_cvt_pk_fp8_f32 v10, v196, v197 op_sel:[0,0,1]
	v_cvt_pk_fp8_f32 v11, v200, v201 op_sel:[0,0,1]
	s_waitcnt lgkmcnt(0)
	s_nop 0
	v_mfma_f32_16x16x32_fp8_fp8 v[60:63], v[76:77], v[10:11], v[60:63]
	ds_read2_b32 v[76:77], v113 offset0:96 offset1:100
	s_waitcnt lgkmcnt(0)
	v_mfma_f32_16x16x32_fp8_fp8 v[76:79], v[76:77], v[10:11], v[64:67]
	s_nop 2
	ds_read2_b32 v[64:65], v114 offset0:160 offset1:164
	s_waitcnt lgkmcnt(0)
	v_mfma_f32_16x16x32_fp8_fp8 v[66:69], v[64:65], v[10:11], v[68:71]
	ds_read2_b32 v[64:65], v115 offset0:224 offset1:228
	s_waitcnt lgkmcnt(0)
	v_mfma_f32_16x16x32_fp8_fp8 v[70:73], v[64:65], v[10:11], v[72:75]
	v_add_f32_e32 v64, v202, v203
	v_div_scale_f32 v10, s[6:7], v64, v64, 1.0
	v_rcp_f32_e32 v11, v10
	s_nop 0
	v_fma_f32 v65, -v10, v11, 1.0
	v_fmac_f32_e32 v11, v65, v11
	v_div_scale_f32 v65, vcc, 1.0, v64, 1.0
	v_mul_f32_e32 v74, v65, v11
	v_fma_f32 v75, -v10, v74, v65
	v_fmac_f32_e32 v74, v75, v11
	v_fma_f32 v10, -v10, v74, v65
	v_div_fmas_f32 v10, v10, v11, v74
	v_div_fixup_f32 v10, v10, v64, 1.0
	v_mul_f32_e32 v11, v10, v60
	v_mul_f32_e32 v60, v10, v61
	v_med3_f32 v11, v11, s81, v185
	v_med3_f32 v60, v60, s81, v185
	v_mov_b32_e32 v61, v8
	v_cvt_pk_fp8_f32 v61, v11, v60
	v_mul_f32_e32 v11, v10, v62
	v_mul_f32_e32 v60, v10, v63
	v_med3_f32 v11, v11, s81, v185
	v_med3_f32 v60, v60, s81, v185
	v_cvt_pk_fp8_f32 v61, v11, v60 op_sel:[0,0,1]
	v_mul_f32_e32 v11, v10, v76
	v_mul_f32_e32 v60, v10, v77
	v_med3_f32 v11, v11, s81, v185
	v_med3_f32 v60, v60, s81, v185
	v_mov_b32_e32 v62, v8
	v_cvt_pk_fp8_f32 v62, v11, v60
	v_mul_f32_e32 v11, v10, v78
	v_mul_f32_e32 v60, v10, v79
	v_med3_f32 v11, v11, s81, v185
	v_med3_f32 v60, v60, s81, v185
	v_cvt_pk_fp8_f32 v62, v11, v60 op_sel:[0,0,1]
	v_mul_f32_e32 v11, v10, v66
	v_mul_f32_e32 v60, v10, v67
	v_med3_f32 v11, v11, s81, v185
	ds_write2_b32 v181, v61, v62 offset1:4
	v_med3_f32 v60, v60, s81, v185
	v_mov_b32_e32 v61, v8
	v_cvt_pk_fp8_f32 v61, v11, v60
	v_mul_f32_e32 v11, v10, v68
	v_mul_f32_e32 v60, v10, v69
	v_med3_f32 v11, v11, s81, v185
	v_med3_f32 v60, v60, s81, v185
	v_cvt_pk_fp8_f32 v61, v11, v60 op_sel:[0,0,1]
	v_mul_f32_e32 v11, v10, v70
	v_mul_f32_e32 v60, v10, v71
	v_med3_f32 v11, v11, s81, v185
	v_med3_f32 v60, v60, s81, v185
	v_mov_b32_e32 v62, v8
	v_cvt_pk_fp8_f32 v62, v11, v60
	v_mul_f32_e32 v11, v10, v72
	v_mul_f32_e32 v10, v10, v73
	v_med3_f32 v11, v11, s81, v185
	v_med3_f32 v10, v10, s81, v185
	v_cvt_pk_fp8_f32 v62, v11, v10 op_sel:[0,0,1]
	v_lshl_add_u32 v10, s86, 7, v124
	v_lshlrev_b32_e32 v10, s1, v10
	v_add_u32_e32 v10, s5, v10
	s_ashr_i32 s5, s4, 31
	s_ashr_i32 s1, s0, 31
	s_lshl_b64 s[4:5], s[4:5], 15
	s_lshl_b64 s[0:1], s[0:1], 11
	ds_write2_b32 v181, v61, v62 offset0:8 offset1:12
	s_add_u32 s0, s4, s0
	s_waitcnt lgkmcnt(0)
	s_addc_u32 s1, s5, s1
	v_ashrrev_i32_e32 v11, 31, v10
	ds_read_b128 v[60:63], v182
	v_lshl_add_u64 v[10:11], s[0:1], 0, v[10:11]
	v_lshlrev_b64 v[10:11], 8, v[10:11]
	v_lshl_add_u64 v[10:11], s[94:95], 0, v[10:11]
	s_lshl_b32 s86, s11, 6
	v_lshl_add_u64 v[10:11], v[10:11], 0, s[86:87]
	v_lshl_add_u64 v[10:11], v[10:11], 0, v[84:85]
	s_waitcnt lgkmcnt(0)
	global_store_dwordx4 v[10:11], v[60:63], off
	s_mov_b64 s[0:1], exec
	v_readlane_b32 s4, v250, 35
	v_readlane_b32 s5, v250, 36
	s_and_b64 s[4:5], s[0:1], s[4:5]
	s_mov_b64 exec, s[4:5]
	s_cbranch_execz .LBB0_286
	v_log_f32_e32 v10, v64
	s_nop 0
	v_add_f32_e32 v9, v9, v10
	v_mul_f32_e32 v9, 0x3f317218, v9
	global_store_dword v[98:99], v9, off
